# v21: v19 + priority raise for waves 4-7 during the SwiGLU epilogue
# speedup vs baseline: 1.0020x; 1.0020x over previous
;     __device__ __forceinline__ void operator()(const f32x4 (&acc)[2][2][4][2], const Unit& u, int wr, int wc, int fr, int fq) const {
;         const int row0 = u.pm * BM + wr * 64 + fr, col0 = u.pn * HALF + wc * 32 + 8 * fq;
.LBB0_704:
	s_cmp_eq_u64 s[16:17], 0
	s_cbranch_scc0 .Lswi_prio_done
	s_setprio 1
